# grid-barrier poll loops spin without s_sleep (waiting waves stay active)
# speedup vs baseline: 1.0062x; 1.0062x over previous
; __global__ void __launch_bounds__(NWAVES * 64, 2) fwd_megakernel(Args args) {
;     ...
;     if (hi > 1000) cg::this_grid().sync();
.LBB0_43:
	global_load_dword v2, v1, s[6:7] offset:32 sc1
	s_waitcnt vmcnt(0)
	v_and_b32_e32 v2, 0xffff0000, v2
	v_cmp_ne_u32_e32 vcc, v2, v0
	s_or_b64 s[8:9], vcc, s[8:9]
	s_andn2_b64 exec, exec, s[8:9]
	s_cbranch_execnz .LBB0_43

; __device__ __forceinline__ unsigned xb_ld(unsigned* p)              { return __hip_atomic_load(p, __ATOMIC_RELAXED, __HIP_MEMORY_SCOPE_AGENT); }
; __device__ __forceinline__ void xcd_barrier_complete(unsigned* bar, unsigned x, unsigned& nloc, unsigned& nx) {
;     ...
;     for (;;) {
;         sum = 0u; cnt = 0u; mine = 0u;
; #pragma unroll
;         for (unsigned j = 0; j < 16; ++j) { const unsigned c = xb_ld(&bar[XB_XCNT(j)]); sum += c; cnt += (c > 0u) ? 1u : 0u; mine = (j == x) ? c : mine; }
;         if (sum == G) break;
;         __builtin_amdgcn_s_sleep(1);
;         if ((++sp & 255u) == 0u) { if (xb_ld(&bar[XB_TMO])) break; if (sp > XB_SPIN_CAP) { atomicAdd(&bar[XB_TMO], 1u); break; } }
;     }
.LBB0_151:
	global_load_dword v15, v16, s[90:91] offset:1024 sc1
	global_load_dword v0, v16, s[90:91] offset:1280 sc1
	global_load_dword v1, v16, s[90:91] offset:1536 sc1
	global_load_dword v2, v16, s[90:91] offset:1792 sc1
	global_load_dword v3, v16, s[90:91] offset:2048 sc1
	global_load_dword v4, v16, s[90:91] offset:2304 sc1
	global_load_dword v5, v16, s[90:91] offset:2560 sc1
	global_load_dword v6, v16, s[90:91] offset:2816 sc1
	global_load_dword v7, v16, s[90:91] offset:3072 sc1
	global_load_dword v8, v16, s[90:91] offset:3328 sc1
	global_load_dword v9, v16, s[90:91] offset:3584 sc1
	global_load_dword v10, v16, s[90:91] offset:3840 sc1
	global_load_dword v11, v16, s[6:7] sc1
	global_load_dword v12, v16, s[20:21] sc1
	global_load_dword v13, v16, s[22:23] sc1
	global_load_dword v14, v16, s[24:25] sc1
	s_mov_b64 s[26:27], -1
	s_mov_b64 s[28:29], -1
	s_waitcnt vmcnt(14)
	v_add_u32_e32 v17, v0, v15
	s_waitcnt vmcnt(13)
	v_add_u32_e32 v17, v17, v1
	s_waitcnt vmcnt(12)
	v_add_u32_e32 v17, v17, v2
	s_waitcnt vmcnt(11)
	v_add_u32_e32 v17, v17, v3
	s_waitcnt vmcnt(10)
	v_add_u32_e32 v17, v17, v4
	s_waitcnt vmcnt(9)
	v_add_u32_e32 v17, v17, v5
	s_waitcnt vmcnt(8)
	v_add_u32_e32 v17, v17, v6
	s_waitcnt vmcnt(7)
	v_add_u32_e32 v17, v17, v7
	s_waitcnt vmcnt(6)
	v_add_u32_e32 v17, v17, v8
	s_waitcnt vmcnt(5)
	v_add_u32_e32 v17, v17, v9
	s_waitcnt vmcnt(4)
	v_add_u32_e32 v17, v17, v10
	s_waitcnt vmcnt(3)
	v_add_u32_e32 v17, v17, v11
	s_waitcnt vmcnt(2)
	v_add_u32_e32 v17, v17, v12
	s_waitcnt vmcnt(1)
	v_add_u32_e32 v17, v17, v13
	s_waitcnt vmcnt(0)
	v_add_u32_e32 v17, v17, v14
	v_cmp_eq_u32_e32 vcc, s2, v17
	s_cbranch_vccnz .LBB0_150
	s_and_b32 s11, s10, 0xff
	s_cmp_eq_u32 s11, 0
	s_mov_b64 s[30:31], -1
	s_cbranch_scc0 .LBB0_155
	global_load_dword v17, v16, s[90:91] offset:512 sc1
	s_waitcnt vmcnt(0)
	v_cmp_eq_u32_e32 vcc, 0, v17
	s_cbranch_vccnz .LBB0_157
	s_mov_b64 s[30:31], 0

.LBB0_169:
	s_and_b32 s10, s2, 0xff
	s_mov_b64 s[30:31], -1
	s_cmp_lg_u32 s10, 0
	s_mov_b64 s[36:37], -1
	s_cbranch_scc1 .LBB0_172
	global_load_dword v2, v0, s[90:91] offset:512 sc1
	s_waitcnt vmcnt(0)
	v_cmp_eq_u32_e32 vcc, 0, v2
	s_cbranch_vccnz .LBB0_174
	s_mov_b64 s[36:37], 0
	s_mov_b64 s[34:35], -1

.LBB0_186:
	s_and_b32 s10, s2, 0xff
	s_cmp_lg_u32 s10, 0
	s_mov_b64 s[36:37], -1
	s_cbranch_scc1 .LBB0_189
	global_load_dword v1, v0, s[24:25] sc1
	s_waitcnt vmcnt(0)
	v_cmp_eq_u32_e32 vcc, 0, v1
	s_cbranch_vccnz .LBB0_191
	s_mov_b64 s[36:37], 0
	s_mov_b64 s[34:35], -1

; __device__ __forceinline__ unsigned xb_ld(unsigned* p)              { return __hip_atomic_load(p, __ATOMIC_RELAXED, __HIP_MEMORY_SCOPE_AGENT); }
; __device__ __forceinline__ void xcd_barrier_complete(unsigned* bar, unsigned x, unsigned& nloc, unsigned& nx) {
;     ...
;     for (;;) {
;         sum = 0u; cnt = 0u; mine = 0u;
; #pragma unroll
;         for (unsigned j = 0; j < 16; ++j) { const unsigned c = xb_ld(&bar[XB_XCNT(j)]); sum += c; cnt += (c > 0u) ? 1u : 0u; mine = (j == x) ? c : mine; }
;         if (sum == G) break;
;         __builtin_amdgcn_s_sleep(1);
;         if ((++sp & 255u) == 0u) { if (xb_ld(&bar[XB_TMO])) break; if (sp > XB_SPIN_CAP) { atomicAdd(&bar[XB_TMO], 1u); break; } }
;     }
.LBB0_289:
	global_load_dword v15, v16, s[90:91] offset:1024 sc1
	global_load_dword v0, v16, s[90:91] offset:1280 sc1
	global_load_dword v1, v16, s[90:91] offset:1536 sc1
	global_load_dword v2, v16, s[90:91] offset:1792 sc1
	global_load_dword v3, v16, s[90:91] offset:2048 sc1
	global_load_dword v4, v16, s[90:91] offset:2304 sc1
	global_load_dword v5, v16, s[90:91] offset:2560 sc1
	global_load_dword v6, v16, s[90:91] offset:2816 sc1
	global_load_dword v7, v16, s[90:91] offset:3072 sc1
	global_load_dword v8, v16, s[90:91] offset:3328 sc1
	global_load_dword v9, v16, s[90:91] offset:3584 sc1
	global_load_dword v10, v16, s[90:91] offset:3840 sc1
	global_load_dword v11, v16, s[18:19] sc1
	global_load_dword v12, v16, s[20:21] sc1
	global_load_dword v13, v16, s[22:23] sc1
	global_load_dword v14, v16, s[24:25] sc1
	s_mov_b64 s[26:27], -1
	s_mov_b64 s[28:29], -1
	s_waitcnt vmcnt(14)
	v_add_u32_e32 v17, v0, v15
	s_waitcnt vmcnt(13)
	v_add_u32_e32 v17, v17, v1
	s_waitcnt vmcnt(12)
	v_add_u32_e32 v17, v17, v2
	s_waitcnt vmcnt(11)
	v_add_u32_e32 v17, v17, v3
	s_waitcnt vmcnt(10)
	v_add_u32_e32 v17, v17, v4
	s_waitcnt vmcnt(9)
	v_add_u32_e32 v17, v17, v5
	s_waitcnt vmcnt(8)
	v_add_u32_e32 v17, v17, v6
	s_waitcnt vmcnt(7)
	v_add_u32_e32 v17, v17, v7
	s_waitcnt vmcnt(6)
	v_add_u32_e32 v17, v17, v8
	s_waitcnt vmcnt(5)
	v_add_u32_e32 v17, v17, v9
	s_waitcnt vmcnt(4)
	v_add_u32_e32 v17, v17, v10
	s_waitcnt vmcnt(3)
	v_add_u32_e32 v17, v17, v11
	s_waitcnt vmcnt(2)
	v_add_u32_e32 v17, v17, v12
	s_waitcnt vmcnt(1)
	v_add_u32_e32 v17, v17, v13
	s_waitcnt vmcnt(0)
	v_add_u32_e32 v17, v17, v14
	v_cmp_eq_u32_e32 vcc, s2, v17
	s_cbranch_vccnz .LBB0_288
	s_and_b32 s12, s10, 0xff
	s_cmp_eq_u32 s12, 0
	s_mov_b64 s[30:31], -1
	s_cbranch_scc0 .LBB0_293
	global_load_dword v17, v16, s[90:91] offset:512 sc1
	s_waitcnt vmcnt(0)
	v_cmp_eq_u32_e32 vcc, 0, v17
	s_cbranch_vccnz .LBB0_295
	s_mov_b64 s[30:31], 0

; __device__ __forceinline__ unsigned xb_ld(unsigned* p)              { return __hip_atomic_load(p, __ATOMIC_RELAXED, __HIP_MEMORY_SCOPE_AGENT); }
; __device__ __forceinline__ void xcd_barrier_complete(unsigned* bar, unsigned x, unsigned& nloc, unsigned& nx) {
;     ...
;     for (;;) {
;         sum = 0u; cnt = 0u; mine = 0u;
; #pragma unroll
;         for (unsigned j = 0; j < 16; ++j) { const unsigned c = xb_ld(&bar[XB_XCNT(j)]); sum += c; cnt += (c > 0u) ? 1u : 0u; mine = (j == x) ? c : mine; }
;         if (sum == G) break;
;         __builtin_amdgcn_s_sleep(1);
;         if ((++sp & 255u) == 0u) { if (xb_ld(&bar[XB_TMO])) break; if (sp > XB_SPIN_CAP) { atomicAdd(&bar[XB_TMO], 1u); break; } }
;     }
.LBB0_457:
	global_load_dword v15, v16, s[90:91] offset:1024 sc1
	global_load_dword v0, v16, s[90:91] offset:1280 sc1
	global_load_dword v1, v16, s[90:91] offset:1536 sc1
	global_load_dword v2, v16, s[90:91] offset:1792 sc1
	global_load_dword v3, v16, s[90:91] offset:2048 sc1
	global_load_dword v4, v16, s[90:91] offset:2304 sc1
	global_load_dword v5, v16, s[90:91] offset:2560 sc1
	global_load_dword v6, v16, s[90:91] offset:2816 sc1
	global_load_dword v7, v16, s[90:91] offset:3072 sc1
	global_load_dword v8, v16, s[90:91] offset:3328 sc1
	global_load_dword v9, v16, s[90:91] offset:3584 sc1
	global_load_dword v10, v16, s[90:91] offset:3840 sc1
	global_load_dword v11, v16, s[6:7] sc1
	global_load_dword v12, v16, s[20:21] sc1
	global_load_dword v13, v16, s[22:23] sc1
	global_load_dword v14, v16, s[24:25] sc1
	s_mov_b64 s[26:27], -1
	s_mov_b64 s[28:29], -1
	s_waitcnt vmcnt(14)
	v_add_u32_e32 v17, v0, v15
	s_waitcnt vmcnt(13)
	v_add_u32_e32 v17, v17, v1
	s_waitcnt vmcnt(12)
	v_add_u32_e32 v17, v17, v2
	s_waitcnt vmcnt(11)
	v_add_u32_e32 v17, v17, v3
	s_waitcnt vmcnt(10)
	v_add_u32_e32 v17, v17, v4
	s_waitcnt vmcnt(9)
	v_add_u32_e32 v17, v17, v5
	s_waitcnt vmcnt(8)
	v_add_u32_e32 v17, v17, v6
	s_waitcnt vmcnt(7)
	v_add_u32_e32 v17, v17, v7
	s_waitcnt vmcnt(6)
	v_add_u32_e32 v17, v17, v8
	s_waitcnt vmcnt(5)
	v_add_u32_e32 v17, v17, v9
	s_waitcnt vmcnt(4)
	v_add_u32_e32 v17, v17, v10
	s_waitcnt vmcnt(3)
	v_add_u32_e32 v17, v17, v11
	s_waitcnt vmcnt(2)
	v_add_u32_e32 v17, v17, v12
	s_waitcnt vmcnt(1)
	v_add_u32_e32 v17, v17, v13
	s_waitcnt vmcnt(0)
	v_add_u32_e32 v17, v17, v14
	v_cmp_eq_u32_e32 vcc, s2, v17
	s_cbranch_vccnz .LBB0_456
	s_and_b32 s12, s10, 0xff
	s_cmp_eq_u32 s12, 0
	s_mov_b64 s[30:31], -1
	s_cbranch_scc0 .LBB0_461
	global_load_dword v17, v16, s[90:91] offset:512 sc1
	s_waitcnt vmcnt(0)
	v_cmp_eq_u32_e32 vcc, 0, v17
	s_cbranch_vccnz .LBB0_463
	s_mov_b64 s[30:31], 0

; __device__ __forceinline__ unsigned xb_ld(unsigned* p)              { return __hip_atomic_load(p, __ATOMIC_RELAXED, __HIP_MEMORY_SCOPE_AGENT); }
; __device__ __forceinline__ void xcd_barrier_complete(unsigned* bar, unsigned x, unsigned& nloc, unsigned& nx) {
;     ...
;     for (;;) {
;         sum = 0u; cnt = 0u; mine = 0u;
; #pragma unroll
;         for (unsigned j = 0; j < 16; ++j) { const unsigned c = xb_ld(&bar[XB_XCNT(j)]); sum += c; cnt += (c > 0u) ? 1u : 0u; mine = (j == x) ? c : mine; }
;         if (sum == G) break;
;         __builtin_amdgcn_s_sleep(1);
;         if ((++sp & 255u) == 0u) { if (xb_ld(&bar[XB_TMO])) break; if (sp > XB_SPIN_CAP) { atomicAdd(&bar[XB_TMO], 1u); break; } }
;     }
.LBB0_660:
	global_load_dword v15, v16, s[90:91] offset:1024 sc1
	global_load_dword v0, v16, s[90:91] offset:1280 sc1
	global_load_dword v1, v16, s[90:91] offset:1536 sc1
	global_load_dword v2, v16, s[90:91] offset:1792 sc1
	global_load_dword v3, v16, s[90:91] offset:2048 sc1
	global_load_dword v4, v16, s[90:91] offset:2304 sc1
	global_load_dword v5, v16, s[90:91] offset:2560 sc1
	global_load_dword v6, v16, s[90:91] offset:2816 sc1
	global_load_dword v7, v16, s[90:91] offset:3072 sc1
	global_load_dword v8, v16, s[90:91] offset:3328 sc1
	global_load_dword v9, v16, s[90:91] offset:3584 sc1
	global_load_dword v10, v16, s[90:91] offset:3840 sc1
	global_load_dword v11, v16, s[16:17] sc1
	global_load_dword v12, v16, s[18:19] sc1
	global_load_dword v13, v16, s[20:21] sc1
	global_load_dword v14, v16, s[22:23] sc1
	s_mov_b64 s[24:25], -1
	s_mov_b64 s[26:27], -1
	s_waitcnt vmcnt(14)
	v_add_u32_e32 v17, v0, v15
	s_waitcnt vmcnt(13)
	v_add_u32_e32 v17, v17, v1
	s_waitcnt vmcnt(12)
	v_add_u32_e32 v17, v17, v2
	s_waitcnt vmcnt(11)
	v_add_u32_e32 v17, v17, v3
	s_waitcnt vmcnt(10)
	v_add_u32_e32 v17, v17, v4
	s_waitcnt vmcnt(9)
	v_add_u32_e32 v17, v17, v5
	s_waitcnt vmcnt(8)
	v_add_u32_e32 v17, v17, v6
	s_waitcnt vmcnt(7)
	v_add_u32_e32 v17, v17, v7
	s_waitcnt vmcnt(6)
	v_add_u32_e32 v17, v17, v8
	s_waitcnt vmcnt(5)
	v_add_u32_e32 v17, v17, v9
	s_waitcnt vmcnt(4)
	v_add_u32_e32 v17, v17, v10
	s_waitcnt vmcnt(3)
	v_add_u32_e32 v17, v17, v11
	s_waitcnt vmcnt(2)
	v_add_u32_e32 v17, v17, v12
	s_waitcnt vmcnt(1)
	v_add_u32_e32 v17, v17, v13
	s_waitcnt vmcnt(0)
	v_add_u32_e32 v17, v17, v14
	v_cmp_eq_u32_e32 vcc, s2, v17
	s_cbranch_vccnz .LBB0_659
	s_and_b32 s12, s10, 0xff
	s_cmp_eq_u32 s12, 0
	s_mov_b64 s[28:29], -1
	s_cbranch_scc0 .LBB0_664
	global_load_dword v17, v16, s[90:91] offset:512 sc1
	s_waitcnt vmcnt(0)
	v_cmp_eq_u32_e32 vcc, 0, v17
	s_cbranch_vccnz .LBB0_666
	s_mov_b64 s[28:29], 0

.LBB0_678:
	s_and_b32 s10, s2, 0xff
	s_mov_b64 s[28:29], -1
	s_cmp_lg_u32 s10, 0
	s_mov_b64 s[34:35], -1
	s_cbranch_scc1 .LBB0_681
	global_load_dword v2, v0, s[90:91] offset:512 sc1
	s_waitcnt vmcnt(0)
	v_cmp_eq_u32_e32 vcc, 0, v2
	s_cbranch_vccnz .LBB0_683
	s_mov_b64 s[34:35], 0
	s_mov_b64 s[30:31], -1

.LBB0_695:
	s_and_b32 s10, s2, 0xff
	s_cmp_lg_u32 s10, 0
	s_mov_b64 s[34:35], -1
	s_cbranch_scc1 .LBB0_698
	global_load_dword v1, v0, s[22:23] sc1
	s_waitcnt vmcnt(0)
	v_cmp_eq_u32_e32 vcc, 0, v1
	s_cbranch_vccnz .LBB0_700
	s_mov_b64 s[34:35], 0
	s_mov_b64 s[30:31], -1

; __device__ __forceinline__ unsigned xb_ld(unsigned* p)              { return __hip_atomic_load(p, __ATOMIC_RELAXED, __HIP_MEMORY_SCOPE_AGENT); }
; __device__ __forceinline__ void xcd_barrier_complete(unsigned* bar, unsigned x, unsigned& nloc, unsigned& nx) {
;     ...
;     for (;;) {
;         sum = 0u; cnt = 0u; mine = 0u;
; #pragma unroll
;         for (unsigned j = 0; j < 16; ++j) { const unsigned c = xb_ld(&bar[XB_XCNT(j)]); sum += c; cnt += (c > 0u) ? 1u : 0u; mine = (j == x) ? c : mine; }
;         if (sum == G) break;
;         __builtin_amdgcn_s_sleep(1);
;         if ((++sp & 255u) == 0u) { if (xb_ld(&bar[XB_TMO])) break; if (sp > XB_SPIN_CAP) { atomicAdd(&bar[XB_TMO], 1u); break; } }
;     }
.LBB0_1145:
	global_load_dword v15, v16, s[90:91] offset:1024 sc1
	global_load_dword v0, v16, s[90:91] offset:1280 sc1
	global_load_dword v1, v16, s[90:91] offset:1536 sc1
	global_load_dword v2, v16, s[90:91] offset:1792 sc1
	global_load_dword v3, v16, s[90:91] offset:2048 sc1
	global_load_dword v4, v16, s[90:91] offset:2304 sc1
	global_load_dword v5, v16, s[90:91] offset:2560 sc1
	global_load_dword v6, v16, s[90:91] offset:2816 sc1
	global_load_dword v7, v16, s[90:91] offset:3072 sc1
	global_load_dword v8, v16, s[90:91] offset:3328 sc1
	global_load_dword v9, v16, s[90:91] offset:3584 sc1
	global_load_dword v10, v16, s[90:91] offset:3840 sc1
	global_load_dword v11, v16, s[8:9] sc1
	global_load_dword v12, v16, s[16:17] sc1
	global_load_dword v13, v16, s[18:19] sc1
	global_load_dword v14, v16, s[20:21] sc1
	s_mov_b64 s[22:23], -1
	s_mov_b64 s[24:25], -1
	s_waitcnt vmcnt(14)
	v_add_u32_e32 v17, v0, v15
	s_waitcnt vmcnt(13)
	v_add_u32_e32 v17, v17, v1
	s_waitcnt vmcnt(12)
	v_add_u32_e32 v17, v17, v2
	s_waitcnt vmcnt(11)
	v_add_u32_e32 v17, v17, v3
	s_waitcnt vmcnt(10)
	v_add_u32_e32 v17, v17, v4
	s_waitcnt vmcnt(9)
	v_add_u32_e32 v17, v17, v5
	s_waitcnt vmcnt(8)
	v_add_u32_e32 v17, v17, v6
	s_waitcnt vmcnt(7)
	v_add_u32_e32 v17, v17, v7
	s_waitcnt vmcnt(6)
	v_add_u32_e32 v17, v17, v8
	s_waitcnt vmcnt(5)
	v_add_u32_e32 v17, v17, v9
	s_waitcnt vmcnt(4)
	v_add_u32_e32 v17, v17, v10
	s_waitcnt vmcnt(3)
	v_add_u32_e32 v17, v17, v11
	s_waitcnt vmcnt(2)
	v_add_u32_e32 v17, v17, v12
	s_waitcnt vmcnt(1)
	v_add_u32_e32 v17, v17, v13
	s_waitcnt vmcnt(0)
	v_add_u32_e32 v17, v17, v14
	v_cmp_eq_u32_e32 vcc, s2, v17
	s_cbranch_vccnz .LBB0_1144
	s_and_b32 s12, s10, 0xff
	s_cmp_eq_u32 s12, 0
	s_mov_b64 s[26:27], -1
	s_cbranch_scc0 .LBB0_1149
	global_load_dword v17, v16, s[90:91] offset:512 sc1
	s_waitcnt vmcnt(0)
	v_cmp_eq_u32_e32 vcc, 0, v17
	s_cbranch_vccnz .LBB0_1151
	s_mov_b64 s[26:27], 0

.LBB0_1164:
	s_and_b32 s10, s2, 0xff
	s_mov_b64 s[26:27], -1
	s_cmp_lg_u32 s10, 0
	s_mov_b64 s[30:31], -1
	s_cbranch_scc1 .LBB0_1167
	global_load_dword v2, v0, s[90:91] offset:512 sc1
	s_waitcnt vmcnt(0)
	v_cmp_eq_u32_e32 vcc, 0, v2
	s_cbranch_vccnz .LBB0_1169
	s_mov_b64 s[30:31], 0
	s_mov_b64 s[28:29], -1

.LBB0_1181:
	s_and_b32 s10, s2, 0xff
	s_cmp_lg_u32 s10, 0
	s_mov_b64 s[30:31], -1
	s_cbranch_scc1 .LBB0_1184
	global_load_dword v1, v0, s[20:21] sc1
	s_waitcnt vmcnt(0)
	v_cmp_eq_u32_e32 vcc, 0, v1
	s_cbranch_vccnz .LBB0_1186
	s_mov_b64 s[30:31], 0
	s_mov_b64 s[28:29], -1

; __device__ __forceinline__ unsigned xb_ld(unsigned* p)              { return __hip_atomic_load(p, __ATOMIC_RELAXED, __HIP_MEMORY_SCOPE_AGENT); }
; __device__ __forceinline__ void xcd_barrier_complete(unsigned* bar, unsigned x, unsigned& nloc, unsigned& nx) {
;     ...
;     for (;;) {
;         sum = 0u; cnt = 0u; mine = 0u;
; #pragma unroll
;         for (unsigned j = 0; j < 16; ++j) { const unsigned c = xb_ld(&bar[XB_XCNT(j)]); sum += c; cnt += (c > 0u) ? 1u : 0u; mine = (j == x) ? c : mine; }
;         if (sum == G) break;
;         __builtin_amdgcn_s_sleep(1);
;         if ((++sp & 255u) == 0u) { if (xb_ld(&bar[XB_TMO])) break; if (sp > XB_SPIN_CAP) { atomicAdd(&bar[XB_TMO], 1u); break; } }
;     }
.LBB0_1351:
	global_load_dword v15, v16, s[90:91] offset:1024 sc1
	global_load_dword v0, v16, s[90:91] offset:1280 sc1
	global_load_dword v1, v16, s[90:91] offset:1536 sc1
	global_load_dword v2, v16, s[90:91] offset:1792 sc1
	global_load_dword v3, v16, s[90:91] offset:2048 sc1
	global_load_dword v4, v16, s[90:91] offset:2304 sc1
	global_load_dword v5, v16, s[90:91] offset:2560 sc1
	global_load_dword v6, v16, s[90:91] offset:2816 sc1
	global_load_dword v7, v16, s[90:91] offset:3072 sc1
	global_load_dword v8, v16, s[90:91] offset:3328 sc1
	global_load_dword v9, v16, s[90:91] offset:3584 sc1
	global_load_dword v10, v16, s[90:91] offset:3840 sc1
	global_load_dword v11, v16, s[12:13] sc1
	global_load_dword v12, v16, s[16:17] sc1
	global_load_dword v13, v16, s[18:19] sc1
	global_load_dword v14, v16, s[20:21] sc1
	s_mov_b64 s[22:23], -1
	s_mov_b64 s[24:25], -1
	s_waitcnt vmcnt(14)
	v_add_u32_e32 v17, v0, v15
	s_waitcnt vmcnt(13)
	v_add_u32_e32 v17, v17, v1
	s_waitcnt vmcnt(12)
	v_add_u32_e32 v17, v17, v2
	s_waitcnt vmcnt(11)
	v_add_u32_e32 v17, v17, v3
	s_waitcnt vmcnt(10)
	v_add_u32_e32 v17, v17, v4
	s_waitcnt vmcnt(9)
	v_add_u32_e32 v17, v17, v5
	s_waitcnt vmcnt(8)
	v_add_u32_e32 v17, v17, v6
	s_waitcnt vmcnt(7)
	v_add_u32_e32 v17, v17, v7
	s_waitcnt vmcnt(6)
	v_add_u32_e32 v17, v17, v8
	s_waitcnt vmcnt(5)
	v_add_u32_e32 v17, v17, v9
	s_waitcnt vmcnt(4)
	v_add_u32_e32 v17, v17, v10
	s_waitcnt vmcnt(3)
	v_add_u32_e32 v17, v17, v11
	s_waitcnt vmcnt(2)
	v_add_u32_e32 v17, v17, v12
	s_waitcnt vmcnt(1)
	v_add_u32_e32 v17, v17, v13
	s_waitcnt vmcnt(0)
	v_add_u32_e32 v17, v17, v14
	v_cmp_eq_u32_e32 vcc, s2, v17
	s_cbranch_vccnz .LBB0_1350
	s_and_b32 s14, s10, 0xff
	s_cmp_eq_u32 s14, 0
	s_mov_b64 s[26:27], -1
	s_cbranch_scc0 .LBB0_1355
	global_load_dword v17, v16, s[90:91] offset:512 sc1
	s_waitcnt vmcnt(0)
	v_cmp_eq_u32_e32 vcc, 0, v17
	s_cbranch_vccnz .LBB0_1357
	s_mov_b64 s[26:27], 0

; __device__ __forceinline__ unsigned xb_ld(unsigned* p)              { return __hip_atomic_load(p, __ATOMIC_RELAXED, __HIP_MEMORY_SCOPE_AGENT); }
; __device__ __forceinline__ void xcd_barrier_complete(unsigned* bar, unsigned x, unsigned& nloc, unsigned& nx) {
;     ...
;     for (;;) {
;         sum = 0u; cnt = 0u; mine = 0u;
; #pragma unroll
;         for (unsigned j = 0; j < 16; ++j) { const unsigned c = xb_ld(&bar[XB_XCNT(j)]); sum += c; cnt += (c > 0u) ? 1u : 0u; mine = (j == x) ? c : mine; }
;         if (sum == G) break;
;         __builtin_amdgcn_s_sleep(1);
;         if ((++sp & 255u) == 0u) { if (xb_ld(&bar[XB_TMO])) break; if (sp > XB_SPIN_CAP) { atomicAdd(&bar[XB_TMO], 1u); break; } }
;     }
.LBB0_1503:
	global_load_dword v15, v16, s[90:91] offset:1024 sc1
	global_load_dword v0, v16, s[90:91] offset:1280 sc1
	global_load_dword v1, v16, s[90:91] offset:1536 sc1
	global_load_dword v2, v16, s[90:91] offset:1792 sc1
	global_load_dword v3, v16, s[90:91] offset:2048 sc1
	global_load_dword v4, v16, s[90:91] offset:2304 sc1
	global_load_dword v5, v16, s[90:91] offset:2560 sc1
	global_load_dword v6, v16, s[90:91] offset:2816 sc1
	global_load_dword v7, v16, s[90:91] offset:3072 sc1
	global_load_dword v8, v16, s[90:91] offset:3328 sc1
	global_load_dword v9, v16, s[90:91] offset:3584 sc1
	global_load_dword v10, v16, s[90:91] offset:3840 sc1
	global_load_dword v11, v16, s[12:13] sc1
	global_load_dword v12, v16, s[16:17] sc1
	global_load_dword v13, v16, s[18:19] sc1
	global_load_dword v14, v16, s[20:21] sc1
	s_mov_b64 s[22:23], -1
	s_mov_b64 s[24:25], -1
	s_waitcnt vmcnt(14)
	v_add_u32_e32 v17, v0, v15
	s_waitcnt vmcnt(13)
	v_add_u32_e32 v17, v17, v1
	s_waitcnt vmcnt(12)
	v_add_u32_e32 v17, v17, v2
	s_waitcnt vmcnt(11)
	v_add_u32_e32 v17, v17, v3
	s_waitcnt vmcnt(10)
	v_add_u32_e32 v17, v17, v4
	s_waitcnt vmcnt(9)
	v_add_u32_e32 v17, v17, v5
	s_waitcnt vmcnt(8)
	v_add_u32_e32 v17, v17, v6
	s_waitcnt vmcnt(7)
	v_add_u32_e32 v17, v17, v7
	s_waitcnt vmcnt(6)
	v_add_u32_e32 v17, v17, v8
	s_waitcnt vmcnt(5)
	v_add_u32_e32 v17, v17, v9
	s_waitcnt vmcnt(4)
	v_add_u32_e32 v17, v17, v10
	s_waitcnt vmcnt(3)
	v_add_u32_e32 v17, v17, v11
	s_waitcnt vmcnt(2)
	v_add_u32_e32 v17, v17, v12
	s_waitcnt vmcnt(1)
	v_add_u32_e32 v17, v17, v13
	s_waitcnt vmcnt(0)
	v_add_u32_e32 v17, v17, v14
	v_cmp_eq_u32_e32 vcc, s2, v17
	s_cbranch_vccnz .LBB0_1502
	s_and_b32 s11, s10, 0xff
	s_cmp_eq_u32 s11, 0
	s_mov_b64 s[26:27], -1
	s_cbranch_scc0 .LBB0_1507
	global_load_dword v17, v16, s[6:7] sc1
	s_waitcnt vmcnt(0)
	v_cmp_eq_u32_e32 vcc, 0, v17
	s_cbranch_vccnz .LBB0_1509
	s_mov_b64 s[26:27], 0

.LBB0_1521:
	s_and_b32 s10, s2, 0xff
	s_mov_b64 s[24:25], -1
	s_cmp_lg_u32 s10, 0
	s_mov_b64 s[28:29], -1
	s_cbranch_scc1 .LBB0_1524
	global_load_dword v2, v0, s[6:7] sc1
	s_waitcnt vmcnt(0)
	v_cmp_eq_u32_e32 vcc, 0, v2
	s_cbranch_vccnz .LBB0_1526
	s_mov_b64 s[28:29], 0
	s_mov_b64 s[26:27], -1

.LBB0_1538:
	s_and_b32 s10, s2, 0xff
	s_cmp_lg_u32 s10, 0
	s_mov_b64 s[28:29], -1
	s_cbranch_scc1 .LBB0_1541
	global_load_dword v1, v0, s[6:7] sc1
	s_waitcnt vmcnt(0)
	v_cmp_eq_u32_e32 vcc, 0, v1
	s_cbranch_vccnz .LBB0_1543
	s_mov_b64 s[28:29], 0
	s_mov_b64 s[26:27], -1
